# q_b and kv_b epilogues: gain / rope-table / k_rope loads hoisted from behind the sum-of-squares block and its barrier to the top of the epilogue
# speedup vs baseline: 1.0039x; 1.0033x over previous
;     __device__ __forceinline__ void operator()(const f32x4 (&acc)[2][2][4][2], const Unit& u, int wr, int wc, int fr, int fq) const {
;         const int h = u.pn, row0 = u.pm * BM + wr * 64 + fr; const bool ropew = wc < 2;
; #pragma unroll
;         for (int ai = 0; ai < 2; ++ai)
; #pragma unroll
;             for (int m = 0; m < 4; ++m) { float s = 0.f;
; #pragma unroll
;                 for (int n = 0; n < 2; ++n) { const f32x4 x = acc[ai][0][m][n]; s += (x[0] * x[0] + x[1] * x[1]) + (x[2] * x[2] + x[3] * x[3]);
;                     if (ropew) { const f32x4 y = acc[ai][1][m][n]; s += (y[0] * y[0] + y[1] * y[1]) + (y[2] * y[2] + y[3] * y[3]); } }
;                 s = sum_rows4(s);
;                 if (fq == 0) part[(wr * 4 + wc) * 128 + ai * 64 + m * 16 + fr] = s; }
;         asm volatile("s_waitcnt lgkmcnt(0)" ::: "memory"); __builtin_amdgcn_s_barrier(); asm volatile("" ::: "memory");
;         const int cn = 32 * wc + 8 * fq, i0 = ropew ? 16 * wc + 4 * fq : 0;
;         const f32x4 g0 = *(const f32x4*)(gq + cn), g1 = *(const f32x4*)(gq + cn + 4), gr1 = *(const f32x4*)(gq + 128 + i0), gr2 = *(const f32x4*)(gq + 160 + i0);
; #pragma unroll
;         for (int ai = 0; ai < 2; ++ai) {
;             f32x4 cv[4], sv[4];
;             if (ropew) {
; #pragma unroll
;                 for (int m = 0; m < 4; ++m) { const size_t row = (size_t)(row0 + ai * HALF + m * 16); cv[m] = *(const f32x4*)(cst + row * 32 + i0); sv[m] = *(const f32x4*)(snt + row * 32 + i0); }
.LBB0_385:
	global_load_dwordx4 v[136:139], v[196:197], off offset:16
	global_load_dwordx4 v[140:143], v[196:197], off
	global_load_dwordx4 v[132:135], v[198:199], off offset:512
	global_load_dwordx4 v[128:131], v[198:199], off offset:640
	v_lshl_add_u32 v212, s75, 8, v195
	v_ashrrev_i32_e32 v213, 31, v212
	v_mov_b32_e32 v176, 0
	v_lshlrev_b64 v[214:215], 7, v[212:213]
	v_or_b32_e32 v220, 16, v212
	v_or_b32_e32 v218, 32, v212
	v_or_b32_e32 v216, 48, v212
	v_mov_b32_e32 v177, 0
	v_mov_b32_e32 v178, 0
	v_mov_b32_e32 v179, 0
	v_mov_b32_e32 v168, 0
	v_mov_b32_e32 v169, 0
	v_mov_b32_e32 v170, 0
	v_mov_b32_e32 v171, v176
	v_mov_b32_e32 v160, v176
	v_mov_b32_e32 v161, v176
	v_mov_b32_e32 v162, v176
	v_mov_b32_e32 v163, v176
	v_mov_b32_e32 v148, v176
	v_mov_b32_e32 v149, v176
	v_mov_b32_e32 v150, v176
	v_mov_b32_e32 v151, v176
	v_mov_b32_e32 v144, 0
	v_mov_b32_e32 v145, 0
	v_mov_b32_e32 v146, 0
	v_mov_b32_e32 v147, 0
	v_mov_b32_e32 v180, 0
	v_mov_b32_e32 v181, 0
	v_mov_b32_e32 v182, 0
	v_mov_b32_e32 v183, 0
	v_mov_b32_e32 v172, 0
	v_mov_b32_e32 v173, 0
	v_mov_b32_e32 v174, 0
	v_mov_b32_e32 v175, v176
	v_mov_b32_e32 v164, v176
	v_mov_b32_e32 v165, v176
	v_mov_b32_e32 v166, v176
	v_mov_b32_e32 v167, v176
	v_mov_b32_e32 v156, v176
	v_mov_b32_e32 v157, v176
	v_mov_b32_e32 v158, v176
	v_mov_b32_e32 v159, v176
	v_mov_b32_e32 v152, 0
	v_mov_b32_e32 v153, 0
	v_mov_b32_e32 v154, 0
	v_mov_b32_e32 v155, 0
	s_andn2_b64 vcc, exec, s[4:5]
	s_cbranch_vccnz .Lqbpre_skip
	v_lshl_add_u64 v[144:145], v[200:201], 0, v[214:215]
	v_ashrrev_i32_e32 v221, 31, v220
	v_ashrrev_i32_e32 v217, 31, v216
	v_lshl_add_u64 v[146:147], v[202:203], 0, v[214:215]
	global_load_dwordx4 v[172:175], v[144:145], off
	global_load_dwordx4 v[168:171], v[146:147], off
	v_lshlrev_b64 v[144:145], 7, v[220:221]
	v_lshlrev_b64 v[148:149], 7, v[216:217]
	v_lshl_add_u64 v[146:147], v[200:201], 0, v[144:145]
	v_lshl_add_u64 v[144:145], v[202:203], 0, v[144:145]
	v_lshl_add_u64 v[150:151], v[200:201], 0, v[148:149]
	v_ashrrev_i32_e32 v219, 31, v218
	v_lshl_add_u64 v[148:149], v[202:203], 0, v[148:149]
	global_load_dwordx4 v[180:183], v[150:151], off
	global_load_dwordx4 v[176:179], v[148:149], off
	global_load_dwordx4 v[164:167], v[146:147], off
	global_load_dwordx4 v[160:163], v[144:145], off
	v_lshlrev_b64 v[144:145], 7, v[218:219]
	v_lshl_add_u64 v[146:147], v[200:201], 0, v[144:145]
	v_lshl_add_u64 v[144:145], v[202:203], 0, v[144:145]
	global_load_dwordx4 v[156:159], v[146:147], off
	global_load_dwordx4 v[148:151], v[144:145], off
.Lqbpre_skip:
	v_mul_f32_e32 v222, v125, v125
	v_mul_f32_e32 v223, v127, v127
	v_fmac_f32_e32 v222, v124, v124
	v_fmac_f32_e32 v223, v126, v126
	v_add_f32_e32 v222, v222, v223
	v_mul_f32_e32 v223, v117, v117
	v_mul_f32_e32 v224, v119, v119
	v_fmac_f32_e32 v223, v116, v116
	v_fmac_f32_e32 v224, v118, v118
	v_add_f32_e32 v223, v223, v224
	v_add_f32_e32 v223, v222, v223
	v_cndmask_b32_e64 v222, v222, v223, s[4:5]
	v_mul_f32_e32 v223, v121, v121
	v_mul_f32_e32 v224, v123, v123
	v_fmac_f32_e32 v223, v120, v120
	v_fmac_f32_e32 v224, v122, v122
	v_add_f32_e32 v223, v223, v224
	v_add_f32_e32 v222, v223, v222
	v_mul_f32_e32 v223, v113, v113
	v_mul_f32_e32 v224, v115, v115
	v_fmac_f32_e32 v223, v112, v112
	v_fmac_f32_e32 v224, v114, v114
	v_add_f32_e32 v223, v223, v224
	v_add_f32_e32 v223, v223, v222
	v_cndmask_b32_e64 v222, v222, v223, s[4:5]
	v_mov_b32_e32 v223, v222
	s_nop 1
	v_permlane16_swap_b32_e32 v222, v223
	v_add_f32_e32 v222, v222, v223
	v_mov_b32_e32 v223, v222
	s_nop 1
	v_permlane32_swap_b32_e32 v222, v223
	s_and_saveexec_b64 s[0:1], s[6:7]
	v_add_f32_e32 v222, v222, v223
	ds_write_b32 v228, v222
	s_or_b64 exec, exec, s[0:1]
	v_mul_f32_e32 v222, v109, v109
	v_mul_f32_e32 v223, v111, v111
	v_fmac_f32_e32 v222, v108, v108
	v_fmac_f32_e32 v223, v110, v110
	v_add_f32_e32 v222, v222, v223
	v_mul_f32_e32 v223, v101, v101
	v_mul_f32_e32 v224, v103, v103
	v_fmac_f32_e32 v223, v100, v100
	v_fmac_f32_e32 v224, v102, v102
	v_add_f32_e32 v223, v223, v224
	v_add_f32_e32 v223, v222, v223
	v_cndmask_b32_e64 v222, v222, v223, s[4:5]
	v_mul_f32_e32 v223, v105, v105
	v_mul_f32_e32 v224, v107, v107
	v_fmac_f32_e32 v223, v104, v104
	v_fmac_f32_e32 v224, v106, v106
	v_add_f32_e32 v223, v223, v224
	v_add_f32_e32 v222, v223, v222
	v_mul_f32_e32 v223, v97, v97
	v_mul_f32_e32 v224, v99, v99
	v_fmac_f32_e32 v223, v96, v96
	v_fmac_f32_e32 v224, v98, v98
	v_add_f32_e32 v223, v223, v224
	v_add_f32_e32 v223, v223, v222
	v_cndmask_b32_e64 v222, v222, v223, s[4:5]
	v_mov_b32_e32 v223, v222
	s_nop 1
	v_permlane16_swap_b32_e32 v222, v223
	v_add_f32_e32 v222, v222, v223
	v_mov_b32_e32 v223, v222
	s_nop 1
	v_permlane32_swap_b32_e32 v222, v223
	s_and_saveexec_b64 s[0:1], s[6:7]
	v_add_f32_e32 v222, v222, v223
	ds_write_b32 v228, v222 offset:64
	s_or_b64 exec, exec, s[0:1]
	v_mul_f32_e32 v222, v93, v93
	v_mul_f32_e32 v223, v95, v95
	v_fmac_f32_e32 v222, v92, v92
	v_fmac_f32_e32 v223, v94, v94
	v_add_f32_e32 v222, v222, v223
	v_mul_f32_e32 v223, v85, v85
	v_mul_f32_e32 v224, v87, v87
	v_fmac_f32_e32 v223, v84, v84
	v_fmac_f32_e32 v224, v86, v86
	v_add_f32_e32 v223, v223, v224
	v_add_f32_e32 v223, v222, v223
	v_cndmask_b32_e64 v222, v222, v223, s[4:5]
	v_mul_f32_e32 v223, v89, v89
	v_mul_f32_e32 v224, v91, v91
	v_fmac_f32_e32 v223, v88, v88
	v_fmac_f32_e32 v224, v90, v90
	v_add_f32_e32 v223, v223, v224
	v_add_f32_e32 v222, v223, v222
	v_mul_f32_e32 v223, v81, v81
	v_mul_f32_e32 v224, v83, v83
	v_fmac_f32_e32 v223, v80, v80
	v_fmac_f32_e32 v224, v82, v82
	v_add_f32_e32 v223, v223, v224
	v_add_f32_e32 v223, v223, v222
	v_cndmask_b32_e64 v222, v222, v223, s[4:5]
	v_mov_b32_e32 v223, v222
	s_nop 1
;     __device__ __forceinline__ void operator()(const f32x4 (&acc)[2][2][4][2], const Unit& u, int wr, int wc, int fr, int fq) const {
;     ...
;             for (int m = 0; m < 4; ++m) { float s = 0.f;
; #pragma unroll
;                 for (int n = 0; n < 2; ++n) { const f32x4 x = acc[ai][0][m][n]; s += (x[0] * x[0] + x[1] * x[1]) + (x[2] * x[2] + x[3] * x[3]);
;                     if (ropew) { const f32x4 y = acc[ai][1][m][n]; s += (y[0] * y[0] + y[1] * y[1]) + (y[2] * y[2] + y[3] * y[3]); } }
;                 s = sum_rows4(s);
;                 if (fq == 0) part[(wr * 4 + wc) * 128 + ai * 64 + m * 16 + fr] = s; }
;         asm volatile("s_waitcnt lgkmcnt(0)" ::: "memory"); __builtin_amdgcn_s_barrier(); asm volatile("" ::: "memory");
;         const int cn = 32 * wc + 8 * fq, i0 = ropew ? 16 * wc + 4 * fq : 0;
;         const f32x4 g0 = *(const f32x4*)(gq + cn), g1 = *(const f32x4*)(gq + cn + 4), gr1 = *(const f32x4*)(gq + 128 + i0), gr2 = *(const f32x4*)(gq + 160 + i0);
; #pragma unroll
;         for (int ai = 0; ai < 2; ++ai) {
;             f32x4 cv[4], sv[4];
;             if (ropew) {
; #pragma unroll
;                 for (int m = 0; m < 4; ++m) { const size_t row = (size_t)(row0 + ai * HALF + m * 16); cv[m] = *(const f32x4*)(cst + row * 32 + i0); sv[m] = *(const f32x4*)(snt + row * 32 + i0); }
	v_permlane16_swap_b32_e32 v222, v223
	v_add_f32_e32 v222, v222, v223
	v_mov_b32_e32 v223, v222
	s_nop 1
	v_permlane32_swap_b32_e32 v222, v223
	s_and_saveexec_b64 s[0:1], s[6:7]
	v_add_f32_e32 v222, v222, v223
	ds_write_b32 v228, v222 offset:128
	s_or_b64 exec, exec, s[0:1]
	v_mul_f32_e32 v222, v77, v77
	v_mul_f32_e32 v223, v79, v79
	v_fmac_f32_e32 v222, v76, v76
	v_fmac_f32_e32 v223, v78, v78
	v_add_f32_e32 v222, v222, v223
	v_mul_f32_e32 v223, v69, v69
	v_mul_f32_e32 v224, v71, v71
	v_fmac_f32_e32 v223, v68, v68
	v_fmac_f32_e32 v224, v70, v70
	v_add_f32_e32 v223, v223, v224
	v_add_f32_e32 v223, v222, v223
	v_cndmask_b32_e64 v222, v222, v223, s[4:5]
	v_mul_f32_e32 v223, v73, v73
	v_mul_f32_e32 v224, v75, v75
	v_fmac_f32_e32 v223, v72, v72
	v_fmac_f32_e32 v224, v74, v74
	v_add_f32_e32 v223, v223, v224
	v_add_f32_e32 v222, v223, v222
	v_mul_f32_e32 v223, v65, v65
	v_mul_f32_e32 v224, v67, v67
	v_fmac_f32_e32 v223, v64, v64
	v_fmac_f32_e32 v224, v66, v66
	v_add_f32_e32 v223, v223, v224
	v_add_f32_e32 v223, v223, v222
	v_cndmask_b32_e64 v222, v222, v223, s[4:5]
	v_mov_b32_e32 v223, v222
	s_nop 1
	v_permlane16_swap_b32_e32 v222, v223
	v_add_f32_e32 v222, v222, v223
	v_mov_b32_e32 v223, v222
	s_nop 1
	v_permlane32_swap_b32_e32 v222, v223
	s_and_saveexec_b64 s[0:1], s[6:7]
	v_add_f32_e32 v222, v222, v223
	ds_write_b32 v228, v222 offset:192
	s_or_b64 exec, exec, s[0:1]
	v_mul_f32_e32 v222, v61, v61
	v_mul_f32_e32 v223, v63, v63
	v_fmac_f32_e32 v222, v60, v60
	v_fmac_f32_e32 v223, v62, v62
	v_add_f32_e32 v222, v222, v223
	v_mul_f32_e32 v223, v53, v53
	v_mul_f32_e32 v224, v55, v55
	v_fmac_f32_e32 v223, v52, v52
	v_fmac_f32_e32 v224, v54, v54
	v_add_f32_e32 v223, v223, v224
	v_add_f32_e32 v223, v222, v223
	v_cndmask_b32_e64 v222, v222, v223, s[4:5]
	v_mul_f32_e32 v223, v57, v57
	v_mul_f32_e32 v224, v59, v59
	v_fmac_f32_e32 v223, v56, v56
	v_fmac_f32_e32 v224, v58, v58
	v_add_f32_e32 v223, v223, v224
	v_add_f32_e32 v222, v223, v222
	v_mul_f32_e32 v223, v49, v49
	v_mul_f32_e32 v224, v51, v51
	v_fmac_f32_e32 v223, v48, v48
	v_fmac_f32_e32 v224, v50, v50
	v_add_f32_e32 v223, v223, v224
	v_add_f32_e32 v223, v223, v222
	v_cndmask_b32_e64 v222, v222, v223, s[4:5]
	v_mov_b32_e32 v223, v222
	s_nop 1
	v_permlane16_swap_b32_e32 v222, v223
	v_add_f32_e32 v222, v222, v223
	v_mov_b32_e32 v223, v222
	s_nop 1
	v_permlane32_swap_b32_e32 v222, v223
	s_and_saveexec_b64 s[0:1], s[6:7]
	v_add_f32_e32 v222, v222, v223
	ds_write_b32 v228, v222 offset:256
	s_or_b64 exec, exec, s[0:1]
	v_mul_f32_e32 v222, v45, v45
	v_mul_f32_e32 v223, v47, v47
	v_fmac_f32_e32 v222, v44, v44
	v_fmac_f32_e32 v223, v46, v46
	v_add_f32_e32 v222, v222, v223
	v_mul_f32_e32 v223, v37, v37
	v_mul_f32_e32 v224, v39, v39
	v_fmac_f32_e32 v223, v36, v36
	v_fmac_f32_e32 v224, v38, v38
	v_add_f32_e32 v223, v223, v224
	v_add_f32_e32 v223, v222, v223
	v_cndmask_b32_e64 v222, v222, v223, s[4:5]
	v_mul_f32_e32 v223, v41, v41
	v_mul_f32_e32 v224, v43, v43
	v_fmac_f32_e32 v223, v40, v40
	v_fmac_f32_e32 v224, v42, v42
	v_add_f32_e32 v223, v223, v224
	v_add_f32_e32 v222, v223, v222
	v_mul_f32_e32 v223, v33, v33
	v_mul_f32_e32 v224, v35, v35
	v_fmac_f32_e32 v223, v32, v32
	v_fmac_f32_e32 v224, v34, v34
	v_add_f32_e32 v223, v223, v224
	v_add_f32_e32 v223, v223, v222
	v_cndmask_b32_e64 v222, v222, v223, s[4:5]
	v_mov_b32_e32 v223, v222
	s_nop 1
	v_permlane16_swap_b32_e32 v222, v223
	v_add_f32_e32 v222, v222, v223
	v_mov_b32_e32 v223, v222
	s_nop 1
	v_permlane32_swap_b32_e32 v222, v223
	s_and_saveexec_b64 s[0:1], s[6:7]
	v_add_f32_e32 v222, v222, v223
	ds_write_b32 v228, v222 offset:320
	s_or_b64 exec, exec, s[0:1]
	v_mul_f32_e32 v222, v29, v29
	v_mul_f32_e32 v223, v31, v31
	v_fmac_f32_e32 v222, v28, v28
	v_fmac_f32_e32 v223, v30, v30
	v_add_f32_e32 v222, v222, v223
	v_mul_f32_e32 v223, v21, v21
	v_mul_f32_e32 v224, v23, v23
	v_fmac_f32_e32 v223, v20, v20
	v_fmac_f32_e32 v224, v22, v22
	v_add_f32_e32 v223, v223, v224
	v_add_f32_e32 v223, v222, v223
	v_cndmask_b32_e64 v222, v222, v223, s[4:5]
	v_mul_f32_e32 v223, v25, v25
	v_mul_f32_e32 v224, v27, v27
	v_fmac_f32_e32 v223, v24, v24
	v_fmac_f32_e32 v224, v26, v26
	v_add_f32_e32 v223, v223, v224
	v_add_f32_e32 v222, v223, v222
	v_mul_f32_e32 v223, v17, v17
	v_mul_f32_e32 v224, v19, v19
	v_fmac_f32_e32 v223, v16, v16
	v_fmac_f32_e32 v224, v18, v18
	v_add_f32_e32 v223, v223, v224
	v_add_f32_e32 v223, v223, v222
	v_cndmask_b32_e64 v222, v222, v223, s[4:5]
	v_mov_b32_e32 v223, v222
	s_nop 1
	v_permlane16_swap_b32_e32 v222, v223
	v_add_f32_e32 v222, v222, v223
	v_mov_b32_e32 v223, v222
	s_nop 1
	v_permlane32_swap_b32_e32 v222, v223
	s_and_saveexec_b64 s[0:1], s[6:7]
	v_add_f32_e32 v222, v222, v223
	ds_write_b32 v228, v222 offset:384
	s_or_b64 exec, exec, s[0:1]
	v_mul_f32_e32 v222, v13, v13
	v_mul_f32_e32 v223, v15, v15
	v_fmac_f32_e32 v222, v12, v12
	v_fmac_f32_e32 v223, v14, v14
	v_add_f32_e32 v222, v222, v223
	v_mul_f32_e32 v223, v5, v5
	v_mul_f32_e32 v224, v7, v7
	v_fmac_f32_e32 v223, v4, v4
	v_fmac_f32_e32 v224, v6, v6
	v_add_f32_e32 v223, v223, v224
	v_add_f32_e32 v223, v222, v223
	v_cndmask_b32_e64 v222, v222, v223, s[4:5]
	v_mul_f32_e32 v223, v9, v9
	v_mul_f32_e32 v224, v11, v11
	v_fmac_f32_e32 v223, v8, v8
	v_fmac_f32_e32 v224, v10, v10
	v_add_f32_e32 v223, v223, v224
	v_add_f32_e32 v222, v223, v222
	v_mul_f32_e32 v223, v1, v1
	v_mul_f32_e32 v224, v3, v3
	v_fmac_f32_e32 v223, v0, v0
	v_fmac_f32_e32 v224, v2, v2
	v_add_f32_e32 v223, v223, v224
	v_add_f32_e32 v223, v223, v222
	v_cndmask_b32_e64 v222, v222, v223, s[4:5]
	v_mov_b32_e32 v223, v222
	s_nop 1
	v_permlane16_swap_b32_e32 v222, v223
	v_add_f32_e32 v222, v222, v223
	v_mov_b32_e32 v223, v222
	s_nop 1
	v_permlane32_swap_b32_e32 v222, v223
	s_and_saveexec_b64 s[0:1], s[6:7]
	v_add_f32_e32 v222, v222, v223
	ds_write_b32 v228, v222 offset:448
	s_or_b64 exec, exec, s[0:1]
	s_waitcnt lgkmcnt(0)
	s_barrier
	v_cndmask_b32_e64 v144, 0, 1, s[4:5]
	v_cmp_ne_u32_e64 s[0:1], 1, v144
	s_andn2_b64 vcc, exec, s[4:5]
	s_cbranch_vccnz .LBB0_403
	s_waitcnt vmcnt(0)
	v_mov_b32_e32 v152, v180
	v_mov_b32_e32 v144, v176
	v_mov_b32_e32 v145, v177
	v_mov_b32_e32 v146, v178
	v_mov_b32_e32 v147, v179
	v_mov_b32_e32 v153, v181
	v_mov_b32_e32 v154, v182
	v_mov_b32_e32 v155, v183

;     __device__ __forceinline__ void operator()(const f32x4 (&acc)[2][2][4][2], const Unit& u, int wr, int wc, int fr, int fq) const {
;         const int h = u.pn, row0 = u.pm * BM + wr * 64 + fr;
; #pragma unroll
;         for (int ai = 0; ai < 2; ++ai)
; #pragma unroll
;             for (int m = 0; m < 4; ++m) { float s = 0.f;
; #pragma unroll
;                 for (int n = 0; n < 2; ++n) { const f32x4 x = acc[ai][0][m][n]; s += (x[0] * x[0] + x[1] * x[1]) + (x[2] * x[2] + x[3] * x[3]); }
;                 s = sum_rows4(s);
;                 if (fq == 0) part[(wr * 4 + wc) * 128 + ai * 64 + m * 16 + fr] = s; }
;         asm volatile("s_waitcnt lgkmcnt(0)" ::: "memory"); __builtin_amdgcn_s_barrier(); asm volatile("" ::: "memory");
;         const int cn = 32 * wc + 8 * fq, i0 = 16 * wc + 4 * fq;
;         const f32x4 g0 = *(const f32x4*)(gk + cn), g1 = *(const f32x4*)(gk + cn + 4);
;         f32x4 krv[2][4]; float kss[2][4];
; #pragma unroll
;         for (int ai = 0; ai < 2; ++ai)
; #pragma unroll
;             for (int m = 0; m < 4; ++m) { const size_t row = (size_t)(row0 + ai * HALF + m * 16); krv[ai][m] = *(const f32x4*)(krr + row * 64 + i0); kss[ai][m] = krss[row]; }
.LBB0_447:
	v_lshl_add_u32 v194, s69, 8, v196
	v_ashrrev_i32_e32 v195, 31, v194
	v_lshl_add_u64 v[218:219], v[194:195], 2, s[10:11]
	global_load_dword v179, v[218:219], off
	v_lshlrev_b64 v[128:129], 8, v[194:195]
	v_lshl_add_u64 v[128:129], v[168:169], 0, v[128:129]
	global_load_dwordx4 v[206:209], v[128:129], off
	global_load_dwordx4 v[132:135], v[166:167], off
	s_nop 0
	global_load_dwordx4 v[128:131], v[166:167], off offset:16
	v_or_b32_e32 v220, 16, v194
	v_ashrrev_i32_e32 v221, 31, v220
	v_lshlrev_b64 v[142:143], 8, v[220:221]
	v_lshl_add_u64 v[142:143], v[168:169], 0, v[142:143]
	v_lshl_add_u64 v[144:145], v[220:221], 2, s[10:11]
	global_load_dwordx4 v[210:213], v[142:143], off
	global_load_dword v227, v[144:145], off
	s_mul_i32 s54, s46, 0xc0
	v_mov_b64_e32 v[182:183], s[6:7]
	v_or_b32_e32 v192, 32, v194
	v_or_b32_e32 v190, 48, v194
	v_add_u32_e32 v188, 0x80, v194
	s_lshl_b32 s48, s46, 8
	v_add_u32_e32 v186, 0x90, v194
	v_add_u32_e32 v184, 0xa0, v194
	s_ashr_i32 s55, s54, 31
	v_mad_i64_i32 v[140:141], s[46:47], v194, s67, v[182:183]
	v_ashrrev_i32_e32 v193, 31, v192
	v_ashrrev_i32_e32 v191, 31, v190
	v_ashrrev_i32_e32 v189, 31, v188
	v_ashrrev_i32_e32 v187, 31, v186
	v_ashrrev_i32_e32 v185, 31, v184
	s_lshl_b64 s[46:47], s[54:55], 1
	v_lshlrev_b64 v[142:143], 8, v[192:193]
	v_lshlrev_b64 v[146:147], 8, v[190:191]
	v_lshlrev_b64 v[150:151], 8, v[188:189]
	v_lshl_add_u64 v[144:145], v[192:193], 2, s[10:11]
	v_lshl_add_u64 v[148:149], v[190:191], 2, s[10:11]
	v_lshlrev_b64 v[152:153], 8, v[186:187]
	v_lshlrev_b64 v[154:155], 8, v[184:185]
	v_lshl_add_u64 v[222:223], v[140:141], 0, s[46:47]
	v_lshl_add_u64 v[140:141], v[168:169], 0, v[142:143]
	v_lshl_add_u64 v[142:143], v[168:169], 0, v[146:147]
	v_lshl_add_u64 v[146:147], v[168:169], 0, v[150:151]
	v_lshl_add_u64 v[224:225], v[168:169], 0, v[152:153]
	global_load_dword v232, v[218:219], off offset:512
	global_load_dword v233, v[218:219], off offset:576
	v_lshl_add_u64 v[228:229], v[168:169], 0, v[154:155]
	global_load_dwordx4 v[214:217], v[140:141], off
	global_load_dword v234, v[144:145], off
	global_load_dwordx4 v[152:155], v[142:143], off
	global_load_dword v235, v[148:149], off
	s_nop 0
	global_load_dwordx4 v[148:151], v[146:147], off
	s_nop 0
	global_load_dwordx4 v[144:147], v[224:225], off
	v_mul_f32_e32 v236, v125, v125
	v_mul_f32_e32 v237, v127, v127
	v_fmac_f32_e32 v236, v124, v124
	v_fmac_f32_e32 v237, v126, v126
	v_add_f32_e32 v236, v236, v237
	v_mul_f32_e32 v237, v121, v121
	v_mul_f32_e32 v238, v123, v123
	v_fmac_f32_e32 v237, v120, v120
	v_fmac_f32_e32 v238, v122, v122
	v_add_f32_e32 v237, v237, v238
	v_add_f32_e32 v236, v236, v237
	v_mov_b32_e32 v237, v236
	s_nop 1
	v_permlane16_swap_b32_e32 v236, v237
	v_add_f32_e32 v236, v236, v237
	v_mov_b32_e32 v237, v236
	s_nop 1
	v_permlane32_swap_b32_e32 v236, v237
	s_and_saveexec_b64 s[100:101], s[0:1]
	v_add_f32_e32 v236, v236, v237
	ds_write_b32 v198, v236
	s_or_b64 exec, exec, s[100:101]
	v_mul_f32_e32 v236, v109, v109
	v_mul_f32_e32 v237, v111, v111
	v_fmac_f32_e32 v236, v108, v108
	v_fmac_f32_e32 v237, v110, v110
	v_add_f32_e32 v236, v236, v237
	v_mul_f32_e32 v237, v105, v105
	v_mul_f32_e32 v238, v107, v107
	v_fmac_f32_e32 v237, v104, v104
	v_fmac_f32_e32 v238, v106, v106
	v_add_f32_e32 v237, v237, v238
	v_add_f32_e32 v236, v236, v237
	v_mov_b32_e32 v237, v236
	s_nop 1
	v_permlane16_swap_b32_e32 v236, v237
	v_add_f32_e32 v236, v236, v237
	v_mov_b32_e32 v237, v236
	s_nop 1
	v_permlane32_swap_b32_e32 v236, v237
	s_and_saveexec_b64 s[100:101], s[0:1]
	v_add_f32_e32 v236, v236, v237
	ds_write_b32 v198, v236 offset:64
	s_or_b64 exec, exec, s[100:101]
	v_mul_f32_e32 v236, v93, v93
	v_mul_f32_e32 v237, v95, v95
	v_fmac_f32_e32 v236, v92, v92
	v_fmac_f32_e32 v237, v94, v94
	v_add_f32_e32 v236, v236, v237
	v_mul_f32_e32 v237, v89, v89
	v_mul_f32_e32 v238, v91, v91
	v_fmac_f32_e32 v237, v88, v88
	v_fmac_f32_e32 v238, v90, v90
	v_add_f32_e32 v237, v237, v238
	v_add_f32_e32 v236, v236, v237
	v_mov_b32_e32 v237, v236
	s_nop 1
	v_permlane16_swap_b32_e32 v236, v237
	v_add_f32_e32 v236, v236, v237
	v_mov_b32_e32 v237, v236
	s_nop 1
	v_permlane32_swap_b32_e32 v236, v237
	s_and_saveexec_b64 s[100:101], s[0:1]
	v_add_f32_e32 v236, v236, v237
	ds_write_b32 v198, v236 offset:128
	s_or_b64 exec, exec, s[100:101]
	v_mul_f32_e32 v236, v77, v77
	v_mul_f32_e32 v237, v79, v79
	v_fmac_f32_e32 v236, v76, v76
	v_fmac_f32_e32 v237, v78, v78
	v_add_f32_e32 v236, v236, v237
	v_mul_f32_e32 v237, v73, v73
	v_mul_f32_e32 v238, v75, v75
	v_fmac_f32_e32 v237, v72, v72
	v_fmac_f32_e32 v238, v74, v74
	v_add_f32_e32 v237, v237, v238
	v_add_f32_e32 v236, v236, v237
	v_mov_b32_e32 v237, v236
	s_nop 1
	v_permlane16_swap_b32_e32 v236, v237
	v_add_f32_e32 v236, v236, v237
	v_mov_b32_e32 v237, v236
	s_nop 1
	v_permlane32_swap_b32_e32 v236, v237
	s_and_saveexec_b64 s[100:101], s[0:1]
	v_add_f32_e32 v236, v236, v237
	ds_write_b32 v198, v236 offset:192
	s_or_b64 exec, exec, s[100:101]
	v_mul_f32_e32 v236, v61, v61
	v_mul_f32_e32 v237, v63, v63
	v_fmac_f32_e32 v236, v60, v60
	v_fmac_f32_e32 v237, v62, v62
	v_add_f32_e32 v236, v236, v237
	v_mul_f32_e32 v237, v57, v57
	v_mul_f32_e32 v238, v59, v59
	v_fmac_f32_e32 v237, v56, v56
	v_fmac_f32_e32 v238, v58, v58
	v_add_f32_e32 v237, v237, v238
	v_add_f32_e32 v236, v236, v237
	v_mov_b32_e32 v237, v236
	s_nop 1
	v_permlane16_swap_b32_e32 v236, v237
	v_add_f32_e32 v236, v236, v237
	v_mov_b32_e32 v237, v236
	s_nop 1
	v_permlane32_swap_b32_e32 v236, v237
	s_and_saveexec_b64 s[100:101], s[0:1]
	v_add_f32_e32 v236, v236, v237
	ds_write_b32 v198, v236 offset:256
	s_or_b64 exec, exec, s[100:101]
	v_mul_f32_e32 v236, v45, v45
;     __device__ __forceinline__ void operator()(const f32x4 (&acc)[2][2][4][2], const Unit& u, int wr, int wc, int fr, int fq) const {
;     ...
;                 for (int n = 0; n < 2; ++n) { const f32x4 x = acc[ai][0][m][n]; s += (x[0] * x[0] + x[1] * x[1]) + (x[2] * x[2] + x[3] * x[3]); }
;                 s = sum_rows4(s);
;                 if (fq == 0) part[(wr * 4 + wc) * 128 + ai * 64 + m * 16 + fr] = s; }
;         asm volatile("s_waitcnt lgkmcnt(0)" ::: "memory"); __builtin_amdgcn_s_barrier(); asm volatile("" ::: "memory");
;         const int cn = 32 * wc + 8 * fq, i0 = 16 * wc + 4 * fq;
;         const f32x4 g0 = *(const f32x4*)(gk + cn), g1 = *(const f32x4*)(gk + cn + 4);
;         f32x4 krv[2][4]; float kss[2][4];
; #pragma unroll
;         for (int ai = 0; ai < 2; ++ai)
; #pragma unroll
;             for (int m = 0; m < 4; ++m) { const size_t row = (size_t)(row0 + ai * HALF + m * 16); krv[ai][m] = *(const f32x4*)(krr + row * 64 + i0); kss[ai][m] = krss[row]; }
; #pragma unroll
;         for (int ai = 0; ai < 2; ++ai)
; #pragma unroll
;             for (int m = 0; m < 4; ++m) { const int r128 = ai * 64 + m * 16 + fr;
;                 const size_t row = (size_t)(row0 + ai * HALF + m * 16);
;                 const float tot = (part[(wr * 4 + 0) * 128 + r128] + part[(wr * 4 + 1) * 128 + r128]) + (part[(wr * 4 + 2) * 128 + r128] + part[(wr * 4 + 3) * 128 + r128]) + kss[ai][m];
;                 const float rk = rsqrtf(tot * (1.f / 192.f) + 1e-6f);
;                 bf16_t* krow = kf + row * 3072 + h * 192;
;                 const f32x4 v0 = acc[ai][0][m][0] * rk * g0, v1 = acc[ai][0][m][1] * rk * g1;
;                 u32x4 w; w.x = cvt_pk_bf16(v0[0], v0[1]); w.y = cvt_pk_bf16(v0[2], v0[3]); w.z = cvt_pk_bf16(v1[0], v1[1]); w.w = cvt_pk_bf16(v1[2], v1[3]);
;                 *(u32x4*)(krow + cn) = w;
;                 const f32x4 kr4 = krv[ai][m] * rk;
;                 u32x2 a; a.x = cvt_pk_bf16(kr4[0], kr4[1]); a.y = cvt_pk_bf16(kr4[2], kr4[3]); *(u32x2*)(krow + 128 + i0) = a;
;                 const f32x4 y0 = acc[ai][1][m][0], y1 = acc[ai][1][m][1];
;                 u32x4 z; z.x = cvt_pk_bf16(y0[0], y0[1]); z.y = cvt_pk_bf16(y0[2], y0[3]); z.z = cvt_pk_bf16(y1[0], y1[1]); z.w = cvt_pk_bf16(y1[2], y1[3]);
;                 *(u32x4*)(vdst + row * 4096 + h * 256 + 128 + cn) = z;
	v_mul_f32_e32 v237, v47, v47
	v_fmac_f32_e32 v236, v44, v44
	v_fmac_f32_e32 v237, v46, v46
	v_add_f32_e32 v236, v236, v237
	v_mul_f32_e32 v237, v41, v41
	v_mul_f32_e32 v238, v43, v43
	v_fmac_f32_e32 v237, v40, v40
	v_fmac_f32_e32 v238, v42, v42
	v_add_f32_e32 v237, v237, v238
	v_add_f32_e32 v236, v236, v237
	v_mov_b32_e32 v237, v236
	s_nop 1
	v_permlane16_swap_b32_e32 v236, v237
	v_add_f32_e32 v236, v236, v237
	v_mov_b32_e32 v237, v236
	s_nop 1
	v_permlane32_swap_b32_e32 v236, v237
	s_and_saveexec_b64 s[100:101], s[0:1]
	v_add_f32_e32 v236, v236, v237
	ds_write_b32 v198, v236 offset:320
	s_or_b64 exec, exec, s[100:101]
	v_mul_f32_e32 v236, v29, v29
	v_mul_f32_e32 v237, v31, v31
	v_fmac_f32_e32 v236, v28, v28
	v_fmac_f32_e32 v237, v30, v30
	v_add_f32_e32 v236, v236, v237
	v_mul_f32_e32 v237, v25, v25
	v_mul_f32_e32 v238, v27, v27
	v_fmac_f32_e32 v237, v24, v24
	v_fmac_f32_e32 v238, v26, v26
	v_add_f32_e32 v237, v237, v238
	v_add_f32_e32 v236, v236, v237
	v_mov_b32_e32 v237, v236
	s_nop 1
	v_permlane16_swap_b32_e32 v236, v237
	v_add_f32_e32 v236, v236, v237
	v_mov_b32_e32 v237, v236
	s_nop 1
	v_permlane32_swap_b32_e32 v236, v237
	s_and_saveexec_b64 s[100:101], s[0:1]
	v_add_f32_e32 v236, v236, v237
	ds_write_b32 v198, v236 offset:384
	s_or_b64 exec, exec, s[100:101]
	v_mul_f32_e32 v236, v13, v13
	v_mul_f32_e32 v237, v15, v15
	v_fmac_f32_e32 v236, v12, v12
	v_fmac_f32_e32 v237, v14, v14
	v_add_f32_e32 v236, v236, v237
	v_mul_f32_e32 v237, v9, v9
	v_mul_f32_e32 v238, v11, v11
	v_fmac_f32_e32 v237, v8, v8
	v_fmac_f32_e32 v238, v10, v10
	v_add_f32_e32 v237, v237, v238
	v_add_f32_e32 v236, v236, v237
	v_mov_b32_e32 v237, v236
	s_nop 1
	v_permlane16_swap_b32_e32 v236, v237
	v_add_f32_e32 v236, v236, v237
	v_mov_b32_e32 v237, v236
	s_nop 1
	v_permlane32_swap_b32_e32 v236, v237
	s_and_saveexec_b64 s[100:101], s[0:1]
	v_add_f32_e32 v236, v236, v237
	ds_write_b32 v198, v236 offset:448
	s_or_b64 exec, exec, s[100:101]
	s_waitcnt lgkmcnt(0)
	s_barrier
	ds_read2st64_b32 v[136:137], v199 offset1:2
	ds_read2st64_b32 v[138:139], v199 offset0:4 offset1:6
	s_waitcnt lgkmcnt(0)
	v_mov_b32_e32 v140, v136
	v_mov_b32_e32 v141, v138
	v_mov_b32_e32 v138, v137
	v_pk_add_f32 v[136:137], v[140:141], v[138:139]
	v_add_u32_e32 v180, 0xb0, v194
	v_add_f32_e32 v136, v136, v137
	v_ashrrev_i32_e32 v181, 31, v180
	v_lshlrev_b64 v[204:205], 8, v[180:181]
	v_lshl_add_u64 v[204:205], v[168:169], 0, v[204:205]
	v_lshl_add_u64 v[230:231], v[222:223], 0, v[164:165]
	s_ashr_i32 s49, s48, 31
	s_lshl_b64 s[48:49], s[48:49], 1
	s_waitcnt vmcnt(0)
	v_add_f32_e32 v136, v179, v136
	v_fmamk_f32 v136, v136, 0x3baaaaab, v203
	v_mul_f32_e32 v137, 0x4b800000, v136
	v_cmp_gt_f32_e32 vcc, s66, v136
	s_nop 1
	v_cndmask_b32_e32 v136, v136, v137, vcc
	v_rsq_f32_e32 v179, v136
	global_load_dwordx4 v[140:143], v[228:229], off
	global_load_dwordx4 v[136:139], v[204:205], off
	s_nop 0
	global_load_dword v205, v[218:219], off offset:640
	global_load_dword v204, v[218:219], off offset:704
	v_mul_f32_e32 v218, 0x45800000, v179
	v_cndmask_b32_e32 v218, v179, v218, vcc
	v_pk_mul_f32 v[120:121], v[120:121], v[218:219] op_sel_hi:[1,0]
	v_pk_mul_f32 v[122:123], v[122:123], v[218:219] op_sel_hi:[1,0]
	v_pk_mul_f32 v[124:125], v[124:125], v[218:219] op_sel_hi:[1,0]
	v_pk_mul_f32 v[126:127], v[126:127], v[218:219] op_sel_hi:[1,0]
	v_pk_mul_f32 v[208:209], v[208:209], v[218:219] op_sel_hi:[1,0]
	v_pk_mul_f32 v[206:207], v[206:207], v[218:219] op_sel_hi:[1,0]
	v_pk_mul_f32 v[218:219], v[130:131], v[122:123]
	v_pk_mul_f32 v[122:123], v[128:129], v[120:121]
	v_pk_mul_f32 v[126:127], v[134:135], v[126:127]
	v_pk_mul_f32 v[124:125], v[132:133], v[124:125]
	v_mov_b32_e32 v179, v165
	v_cvt_pk_bf16_f32 v120, v124, v125
	v_cvt_pk_bf16_f32 v121, v126, v127
	v_cvt_pk_bf16_f32 v122, v122, v123
	v_cvt_pk_bf16_f32 v123, v218, v219
	global_store_dwordx4 v[230:231], v[120:123], off
	v_add_u32_e32 v124, 64, v199
	s_nop 0
	v_lshl_add_u64 v[122:123], v[222:223], 0, v[178:179]
	v_cvt_pk_bf16_f32 v120, v206, v207
	v_cvt_pk_bf16_f32 v121, v208, v209
	global_store_dwordx2 v[122:123], v[120:121], off offset:256
	v_cvt_pk_bf16_f32 v116, v116, v117
	v_cvt_pk_bf16_f32 v117, v118, v119
	v_cvt_pk_bf16_f32 v118, v112, v113
	v_cvt_pk_bf16_f32 v119, v114, v115
	ds_read2_b32 v[112:113], v199 offset0:16 offset1:144
	ds_read2st64_b32 v[114:115], v124 offset0:4 offset1:6
	v_lshlrev_b64 v[120:121], 13, v[194:195]
	v_lshl_add_u64 v[120:121], s[38:39], 0, v[120:121]
	s_waitcnt lgkmcnt(1)
	v_mov_b32_e32 v122, v112
	s_waitcnt lgkmcnt(0)
	v_mov_b32_e32 v123, v114
	v_mov_b32_e32 v114, v113
	v_pk_add_f32 v[112:113], v[122:123], v[114:115]
	s_nop 0
	v_add_f32_e32 v112, v112, v113
	v_add_f32_e32 v112, v227, v112
	v_fmamk_f32 v112, v112, 0x3baaaaab, v203
	v_mul_f32_e32 v113, 0x4b800000, v112
	v_cmp_gt_f32_e32 vcc, s66, v112
	s_nop 1
	v_cndmask_b32_e32 v112, v112, v113, vcc
	v_rsq_f32_e32 v114, v112
	v_lshl_add_u64 v[112:113], v[120:121], 0, s[48:49]
	v_lshl_add_u64 v[112:113], v[112:113], 0, v[164:165]
	global_store_dwordx4 v[112:113], v[116:119], off offset:256
	v_mul_f32_e32 v112, 0x45800000, v114
	v_cndmask_b32_e32 v112, v114, v112, vcc
	v_mad_i64_i32 v[114:115], s[54:55], v220, s67, v[182:183]
	v_pk_mul_f32 v[108:109], v[108:109], v[112:113] op_sel_hi:[1,0]
	v_pk_mul_f32 v[104:105], v[104:105], v[112:113] op_sel_hi:[1,0]
	v_pk_mul_f32 v[106:107], v[106:107], v[112:113] op_sel_hi:[1,0]
	v_lshl_add_u64 v[114:115], v[114:115], 0, s[46:47]
	v_pk_mul_f32 v[110:111], v[110:111], v[112:113] op_sel_hi:[1,0]
	v_pk_mul_f32 v[108:109], v[132:133], v[108:109]
	v_pk_mul_f32 v[116:117], v[130:131], v[106:107]
	v_pk_mul_f32 v[106:107], v[128:129], v[104:105]
	v_pk_mul_f32 v[110:111], v[134:135], v[110:111]
	v_cvt_pk_bf16_f32 v104, v108, v109
	v_lshl_add_u64 v[108:109], v[114:115], 0, v[164:165]
	v_cvt_pk_bf16_f32 v105, v110, v111
	v_cvt_pk_bf16_f32 v106, v106, v107
	v_cvt_pk_bf16_f32 v107, v116, v117
	global_store_dwordx4 v[108:109], v[104:107], off
	v_add_u32_e32 v108, 0x80, v199
	s_nop 0
	v_pk_mul_f32 v[104:105], v[212:213], v[112:113] op_sel_hi:[1,0]
	v_pk_mul_f32 v[106:107], v[210:211], v[112:113] op_sel_hi:[1,0]
	s_nop 0
	v_cvt_pk_bf16_f32 v106, v106, v107
	v_cvt_pk_bf16_f32 v107, v104, v105
	v_lshl_add_u64 v[104:105], v[114:115], 0, v[178:179]
	global_store_dwordx2 v[104:105], v[106:107], off offset:256
	v_cvt_pk_bf16_f32 v100, v100, v101
	v_cvt_pk_bf16_f32 v101, v102, v103
	v_cvt_pk_bf16_f32 v102, v96, v97
	v_cvt_pk_bf16_f32 v103, v98, v99
	ds_read2_b32 v[96:97], v199 offset0:32 offset1:160
	ds_read2st64_b32 v[98:99], v108 offset0:4 offset1:6
	v_lshlrev_b64 v[104:105], 13, v[220:221]
	v_lshl_add_u64 v[104:105], s[38:39], 0, v[104:105]
	s_waitcnt lgkmcnt(1)
; __device__ __forceinline__ unsigned cvt_pk_bf16(float lo, float hi) { unsigned r; asm volatile("v_cvt_pk_bf16_f32 %0, %1, %2" : "=v"(r) : "v"(lo), "v"(hi)); return r; }
;     __device__ __forceinline__ void operator()(const f32x4 (&acc)[2][2][4][2], const Unit& u, int wr, int wc, int fr, int fq) const {
;     ...
;         for (int ai = 0; ai < 2; ++ai)
; #pragma unroll
;             for (int m = 0; m < 4; ++m) { const int r128 = ai * 64 + m * 16 + fr;
;                 const size_t row = (size_t)(row0 + ai * HALF + m * 16);
;                 const float tot = (part[(wr * 4 + 0) * 128 + r128] + part[(wr * 4 + 1) * 128 + r128]) + (part[(wr * 4 + 2) * 128 + r128] + part[(wr * 4 + 3) * 128 + r128]) + kss[ai][m];
;                 const float rk = rsqrtf(tot * (1.f / 192.f) + 1e-6f);
;                 bf16_t* krow = kf + row * 3072 + h * 192;
;                 const f32x4 v0 = acc[ai][0][m][0] * rk * g0, v1 = acc[ai][0][m][1] * rk * g1;
;                 u32x4 w; w.x = cvt_pk_bf16(v0[0], v0[1]); w.y = cvt_pk_bf16(v0[2], v0[3]); w.z = cvt_pk_bf16(v1[0], v1[1]); w.w = cvt_pk_bf16(v1[2], v1[3]);
;                 *(u32x4*)(krow + cn) = w;
;                 const f32x4 kr4 = krv[ai][m] * rk;
;                 u32x2 a; a.x = cvt_pk_bf16(kr4[0], kr4[1]); a.y = cvt_pk_bf16(kr4[2], kr4[3]); *(u32x2*)(krow + 128 + i0) = a;
;                 const f32x4 y0 = acc[ai][1][m][0], y1 = acc[ai][1][m][1];
;                 u32x4 z; z.x = cvt_pk_bf16(y0[0], y0[1]); z.y = cvt_pk_bf16(y0[2], y0[3]); z.z = cvt_pk_bf16(y1[0], y1[1]); z.w = cvt_pk_bf16(y1[2], y1[3]);
;                 *(u32x4*)(vdst + row * 4096 + h * 256 + 128 + cn) = z;
	v_mov_b32_e32 v106, v96
	s_waitcnt lgkmcnt(0)
	v_mov_b32_e32 v107, v98
	v_mov_b32_e32 v98, v97
	v_pk_add_f32 v[96:97], v[106:107], v[98:99]
	s_nop 0
	v_add_f32_e32 v96, v96, v97
	v_add_f32_e32 v96, v234, v96
	v_fmamk_f32 v96, v96, 0x3baaaaab, v203
	v_mul_f32_e32 v97, 0x4b800000, v96
	v_cmp_gt_f32_e32 vcc, s66, v96
	s_nop 1
	v_cndmask_b32_e32 v96, v96, v97, vcc
	v_rsq_f32_e32 v98, v96
	v_lshl_add_u64 v[96:97], v[104:105], 0, s[48:49]
	v_lshl_add_u64 v[96:97], v[96:97], 0, v[164:165]
	global_store_dwordx4 v[96:97], v[100:103], off offset:256
	v_mul_f32_e32 v96, 0x45800000, v98
	v_cndmask_b32_e32 v96, v98, v96, vcc
	v_mad_i64_i32 v[98:99], s[54:55], v192, s67, v[182:183]
	v_pk_mul_f32 v[92:93], v[92:93], v[96:97] op_sel_hi:[1,0]
	v_pk_mul_f32 v[88:89], v[88:89], v[96:97] op_sel_hi:[1,0]
	v_pk_mul_f32 v[90:91], v[90:91], v[96:97] op_sel_hi:[1,0]
	v_lshl_add_u64 v[98:99], v[98:99], 0, s[46:47]
	v_pk_mul_f32 v[94:95], v[94:95], v[96:97] op_sel_hi:[1,0]
	v_pk_mul_f32 v[92:93], v[132:133], v[92:93]
	v_pk_mul_f32 v[100:101], v[130:131], v[90:91]
	v_pk_mul_f32 v[90:91], v[128:129], v[88:89]
	v_pk_mul_f32 v[94:95], v[134:135], v[94:95]
	v_cvt_pk_bf16_f32 v88, v92, v93
	v_lshl_add_u64 v[92:93], v[98:99], 0, v[164:165]
	v_cvt_pk_bf16_f32 v89, v94, v95
	v_cvt_pk_bf16_f32 v90, v90, v91
	v_cvt_pk_bf16_f32 v91, v100, v101
	global_store_dwordx4 v[92:93], v[88:91], off
	v_add_u32_e32 v92, 0xc0, v199
	s_nop 0
	v_pk_mul_f32 v[88:89], v[216:217], v[96:97] op_sel_hi:[1,0]
	v_pk_mul_f32 v[90:91], v[214:215], v[96:97] op_sel_hi:[1,0]
	s_nop 0
	v_cvt_pk_bf16_f32 v90, v90, v91
	v_cvt_pk_bf16_f32 v91, v88, v89
	v_lshl_add_u64 v[88:89], v[98:99], 0, v[178:179]
	global_store_dwordx2 v[88:89], v[90:91], off offset:256
	v_cvt_pk_bf16_f32 v84, v84, v85
	v_cvt_pk_bf16_f32 v85, v86, v87
	v_cvt_pk_bf16_f32 v86, v80, v81
	v_cvt_pk_bf16_f32 v87, v82, v83
	ds_read2_b32 v[80:81], v199 offset0:48 offset1:176
	ds_read2st64_b32 v[82:83], v92 offset0:4 offset1:6
	v_lshlrev_b64 v[88:89], 13, v[192:193]
	v_lshl_add_u64 v[88:89], s[38:39], 0, v[88:89]
	s_waitcnt lgkmcnt(1)
	v_mov_b32_e32 v90, v80
	s_waitcnt lgkmcnt(0)
	v_mov_b32_e32 v91, v82
	v_mov_b32_e32 v82, v81
	v_pk_add_f32 v[80:81], v[90:91], v[82:83]
	s_nop 0
	v_add_f32_e32 v80, v80, v81
	v_add_f32_e32 v80, v235, v80
	v_fmamk_f32 v80, v80, 0x3baaaaab, v203
	v_mul_f32_e32 v81, 0x4b800000, v80
	v_cmp_gt_f32_e32 vcc, s66, v80
	s_nop 1
	v_cndmask_b32_e32 v80, v80, v81, vcc
	v_rsq_f32_e32 v82, v80
	v_lshl_add_u64 v[80:81], v[88:89], 0, s[48:49]
	v_lshl_add_u64 v[80:81], v[80:81], 0, v[164:165]
	global_store_dwordx4 v[80:81], v[84:87], off offset:256
	v_mul_f32_e32 v80, 0x45800000, v82
	v_cndmask_b32_e32 v80, v82, v80, vcc
	v_mad_i64_i32 v[82:83], s[54:55], v190, s67, v[182:183]
	v_pk_mul_f32 v[76:77], v[76:77], v[80:81] op_sel_hi:[1,0]
	v_pk_mul_f32 v[72:73], v[72:73], v[80:81] op_sel_hi:[1,0]
	v_pk_mul_f32 v[74:75], v[74:75], v[80:81] op_sel_hi:[1,0]
	v_lshl_add_u64 v[82:83], v[82:83], 0, s[46:47]
	v_pk_mul_f32 v[78:79], v[78:79], v[80:81] op_sel_hi:[1,0]
	v_pk_mul_f32 v[76:77], v[132:133], v[76:77]
	v_pk_mul_f32 v[84:85], v[130:131], v[74:75]
	v_pk_mul_f32 v[74:75], v[128:129], v[72:73]
	v_pk_mul_f32 v[78:79], v[134:135], v[78:79]
	v_cvt_pk_bf16_f32 v72, v76, v77
	v_lshl_add_u64 v[76:77], v[82:83], 0, v[164:165]
	v_cvt_pk_bf16_f32 v73, v78, v79
	v_cvt_pk_bf16_f32 v74, v74, v75
	v_cvt_pk_bf16_f32 v75, v84, v85
	global_store_dwordx4 v[76:77], v[72:75], off
	s_nop 1
	v_pk_mul_f32 v[72:73], v[154:155], v[80:81] op_sel_hi:[1,0]
	v_pk_mul_f32 v[74:75], v[152:153], v[80:81] op_sel_hi:[1,0]
	s_nop 0
	v_cvt_pk_bf16_f32 v74, v74, v75
	v_cvt_pk_bf16_f32 v75, v72, v73
	v_lshl_add_u64 v[72:73], v[82:83], 0, v[178:179]
	global_store_dwordx2 v[72:73], v[74:75], off offset:256
	v_cvt_pk_bf16_f32 v68, v68, v69
	v_cvt_pk_bf16_f32 v69, v70, v71
	v_cvt_pk_bf16_f32 v70, v64, v65
	v_cvt_pk_bf16_f32 v71, v66, v67
	ds_read2st64_b32 v[64:65], v199 offset0:1 offset1:3
	ds_read2st64_b32 v[66:67], v199 offset0:5 offset1:7
	v_lshlrev_b64 v[72:73], 13, v[190:191]
	v_lshl_add_u64 v[72:73], s[38:39], 0, v[72:73]
	s_waitcnt lgkmcnt(1)
	v_mov_b32_e32 v74, v64
	s_waitcnt lgkmcnt(0)
	v_mov_b32_e32 v75, v66
	v_mov_b32_e32 v66, v65
	v_pk_add_f32 v[64:65], v[74:75], v[66:67]
	s_nop 0
	v_add_f32_e32 v64, v64, v65
	v_add_f32_e32 v64, v232, v64
	v_fmamk_f32 v64, v64, 0x3baaaaab, v203
	v_mul_f32_e32 v65, 0x4b800000, v64
	v_cmp_gt_f32_e32 vcc, s66, v64
	s_nop 1
	v_cndmask_b32_e32 v64, v64, v65, vcc
	v_rsq_f32_e32 v66, v64
	v_lshl_add_u64 v[64:65], v[72:73], 0, s[48:49]
	v_lshl_add_u64 v[64:65], v[64:65], 0, v[164:165]
	global_store_dwordx4 v[64:65], v[68:71], off offset:256
	v_mul_f32_e32 v64, 0x45800000, v66
	v_cndmask_b32_e32 v64, v66, v64, vcc
	v_mad_i64_i32 v[66:67], s[54:55], v188, s67, v[182:183]
	v_pk_mul_f32 v[60:61], v[60:61], v[64:65] op_sel_hi:[1,0]
	v_pk_mul_f32 v[56:57], v[56:57], v[64:65] op_sel_hi:[1,0]
	v_pk_mul_f32 v[58:59], v[58:59], v[64:65] op_sel_hi:[1,0]
	v_lshl_add_u64 v[66:67], v[66:67], 0, s[46:47]
	v_pk_mul_f32 v[62:63], v[62:63], v[64:65] op_sel_hi:[1,0]
	v_pk_mul_f32 v[60:61], v[132:133], v[60:61]
	v_pk_mul_f32 v[68:69], v[130:131], v[58:59]
	v_pk_mul_f32 v[58:59], v[128:129], v[56:57]
	v_pk_mul_f32 v[62:63], v[134:135], v[62:63]
	v_cvt_pk_bf16_f32 v56, v60, v61
	v_lshl_add_u64 v[60:61], v[66:67], 0, v[164:165]
	v_cvt_pk_bf16_f32 v57, v62, v63
	v_cvt_pk_bf16_f32 v58, v58, v59
	v_cvt_pk_bf16_f32 v59, v68, v69
	global_store_dwordx4 v[60:61], v[56:59], off
	s_nop 1
	v_pk_mul_f32 v[56:57], v[150:151], v[64:65] op_sel_hi:[1,0]
	v_pk_mul_f32 v[58:59], v[148:149], v[64:65] op_sel_hi:[1,0]
	s_nop 0
	v_cvt_pk_bf16_f32 v58, v58, v59
	v_cvt_pk_bf16_f32 v59, v56, v57
	v_lshl_add_u64 v[56:57], v[66:67], 0, v[178:179]
	global_store_dwordx2 v[56:57], v[58:59], off offset:256
	v_cvt_pk_bf16_f32 v52, v52, v53
	v_cvt_pk_bf16_f32 v53, v54, v55
	v_cvt_pk_bf16_f32 v54, v48, v49
	v_cvt_pk_bf16_f32 v55, v50, v51
	ds_read2_b32 v[48:49], v199 offset0:80 offset1:208
	ds_read2st64_b32 v[50:51], v124 offset0:5 offset1:7
	v_lshlrev_b64 v[56:57], 13, v[188:189]
	v_lshl_add_u64 v[56:57], s[38:39], 0, v[56:57]
	s_waitcnt lgkmcnt(1)
; __device__ __forceinline__ unsigned cvt_pk_bf16(float lo, float hi) { unsigned r; asm volatile("v_cvt_pk_bf16_f32 %0, %1, %2" : "=v"(r) : "v"(lo), "v"(hi)); return r; }
;     __device__ __forceinline__ void operator()(const f32x4 (&acc)[2][2][4][2], const Unit& u, int wr, int wc, int fr, int fq) const {
;     ...
;         for (int ai = 0; ai < 2; ++ai)
; #pragma unroll
;             for (int m = 0; m < 4; ++m) { const int r128 = ai * 64 + m * 16 + fr;
;                 const size_t row = (size_t)(row0 + ai * HALF + m * 16);
;                 const float tot = (part[(wr * 4 + 0) * 128 + r128] + part[(wr * 4 + 1) * 128 + r128]) + (part[(wr * 4 + 2) * 128 + r128] + part[(wr * 4 + 3) * 128 + r128]) + kss[ai][m];
;                 const float rk = rsqrtf(tot * (1.f / 192.f) + 1e-6f);
;                 bf16_t* krow = kf + row * 3072 + h * 192;
;                 const f32x4 v0 = acc[ai][0][m][0] * rk * g0, v1 = acc[ai][0][m][1] * rk * g1;
;                 u32x4 w; w.x = cvt_pk_bf16(v0[0], v0[1]); w.y = cvt_pk_bf16(v0[2], v0[3]); w.z = cvt_pk_bf16(v1[0], v1[1]); w.w = cvt_pk_bf16(v1[2], v1[3]);
;                 *(u32x4*)(krow + cn) = w;
;                 const f32x4 kr4 = krv[ai][m] * rk;
;                 u32x2 a; a.x = cvt_pk_bf16(kr4[0], kr4[1]); a.y = cvt_pk_bf16(kr4[2], kr4[3]); *(u32x2*)(krow + 128 + i0) = a;
;                 const f32x4 y0 = acc[ai][1][m][0], y1 = acc[ai][1][m][1];
;                 u32x4 z; z.x = cvt_pk_bf16(y0[0], y0[1]); z.y = cvt_pk_bf16(y0[2], y0[3]); z.z = cvt_pk_bf16(y1[0], y1[1]); z.w = cvt_pk_bf16(y1[2], y1[3]);
;                 *(u32x4*)(vdst + row * 4096 + h * 256 + 128 + cn) = z;
	v_mov_b32_e32 v58, v48
	s_waitcnt lgkmcnt(0)
	v_mov_b32_e32 v59, v50
	v_mov_b32_e32 v50, v49
	v_pk_add_f32 v[48:49], v[58:59], v[50:51]
	s_nop 0
	v_add_f32_e32 v48, v48, v49
	v_add_f32_e32 v48, v233, v48
	v_fmamk_f32 v48, v48, 0x3baaaaab, v203
	v_mul_f32_e32 v49, 0x4b800000, v48
	v_cmp_gt_f32_e32 vcc, s66, v48
	s_nop 1
	v_cndmask_b32_e32 v48, v48, v49, vcc
	v_rsq_f32_e32 v50, v48
	v_lshl_add_u64 v[48:49], v[56:57], 0, s[48:49]
	v_lshl_add_u64 v[48:49], v[48:49], 0, v[164:165]
	global_store_dwordx4 v[48:49], v[52:55], off offset:256
	v_mul_f32_e32 v48, 0x45800000, v50
	v_cndmask_b32_e32 v48, v50, v48, vcc
	v_mad_i64_i32 v[50:51], s[54:55], v186, s67, v[182:183]
	v_pk_mul_f32 v[44:45], v[44:45], v[48:49] op_sel_hi:[1,0]
	v_pk_mul_f32 v[40:41], v[40:41], v[48:49] op_sel_hi:[1,0]
	v_pk_mul_f32 v[42:43], v[42:43], v[48:49] op_sel_hi:[1,0]
	v_lshl_add_u64 v[50:51], v[50:51], 0, s[46:47]
	v_pk_mul_f32 v[46:47], v[46:47], v[48:49] op_sel_hi:[1,0]
	v_pk_mul_f32 v[44:45], v[132:133], v[44:45]
	v_pk_mul_f32 v[52:53], v[130:131], v[42:43]
	v_pk_mul_f32 v[42:43], v[128:129], v[40:41]
	v_pk_mul_f32 v[46:47], v[134:135], v[46:47]
	v_cvt_pk_bf16_f32 v40, v44, v45
	v_lshl_add_u64 v[44:45], v[50:51], 0, v[164:165]
	v_cvt_pk_bf16_f32 v41, v46, v47
	v_cvt_pk_bf16_f32 v42, v42, v43
	v_cvt_pk_bf16_f32 v43, v52, v53
	global_store_dwordx4 v[44:45], v[40:43], off
	s_nop 1
	v_pk_mul_f32 v[40:41], v[146:147], v[48:49] op_sel_hi:[1,0]
	v_pk_mul_f32 v[42:43], v[144:145], v[48:49] op_sel_hi:[1,0]
	s_nop 0
	v_cvt_pk_bf16_f32 v42, v42, v43
	v_cvt_pk_bf16_f32 v43, v40, v41
	v_lshl_add_u64 v[40:41], v[50:51], 0, v[178:179]
	global_store_dwordx2 v[40:41], v[42:43], off offset:256
	v_cvt_pk_bf16_f32 v36, v36, v37
	v_cvt_pk_bf16_f32 v37, v38, v39
	v_cvt_pk_bf16_f32 v38, v32, v33
	v_cvt_pk_bf16_f32 v39, v34, v35
	ds_read2_b32 v[32:33], v199 offset0:96 offset1:224
	ds_read2st64_b32 v[34:35], v108 offset0:5 offset1:7
	v_lshlrev_b64 v[40:41], 13, v[186:187]
	v_lshl_add_u64 v[40:41], s[38:39], 0, v[40:41]
	s_waitcnt lgkmcnt(1)
	v_mov_b32_e32 v42, v32
	s_waitcnt lgkmcnt(0)
	v_mov_b32_e32 v43, v34
	v_mov_b32_e32 v34, v33
	v_pk_add_f32 v[32:33], v[42:43], v[34:35]
	s_nop 0
	v_add_f32_e32 v32, v32, v33
	s_waitcnt vmcnt(18)
	v_add_f32_e32 v32, v205, v32
	v_fmamk_f32 v32, v32, 0x3baaaaab, v203
	v_mul_f32_e32 v33, 0x4b800000, v32
	v_cmp_gt_f32_e32 vcc, s66, v32
	s_nop 1
	v_cndmask_b32_e32 v32, v32, v33, vcc
	v_rsq_f32_e32 v34, v32
	v_lshl_add_u64 v[32:33], v[40:41], 0, s[48:49]
	v_lshl_add_u64 v[32:33], v[32:33], 0, v[164:165]
	global_store_dwordx4 v[32:33], v[36:39], off offset:256
	v_mul_f32_e32 v32, 0x45800000, v34
	v_cndmask_b32_e32 v32, v34, v32, vcc
	v_mad_i64_i32 v[34:35], s[54:55], v184, s67, v[182:183]
	v_pk_mul_f32 v[28:29], v[28:29], v[32:33] op_sel_hi:[1,0]
	v_pk_mul_f32 v[24:25], v[24:25], v[32:33] op_sel_hi:[1,0]
	v_pk_mul_f32 v[26:27], v[26:27], v[32:33] op_sel_hi:[1,0]
	v_lshl_add_u64 v[34:35], v[34:35], 0, s[46:47]
	v_pk_mul_f32 v[30:31], v[30:31], v[32:33] op_sel_hi:[1,0]
	v_pk_mul_f32 v[28:29], v[132:133], v[28:29]
	v_pk_mul_f32 v[36:37], v[130:131], v[26:27]
	v_pk_mul_f32 v[26:27], v[128:129], v[24:25]
	v_pk_mul_f32 v[30:31], v[134:135], v[30:31]
	v_cvt_pk_bf16_f32 v24, v28, v29
	v_lshl_add_u64 v[28:29], v[34:35], 0, v[164:165]
	v_cvt_pk_bf16_f32 v25, v30, v31
	v_cvt_pk_bf16_f32 v26, v26, v27
	v_cvt_pk_bf16_f32 v27, v36, v37
	global_store_dwordx4 v[28:29], v[24:27], off
	s_nop 1
	v_pk_mul_f32 v[24:25], v[142:143], v[32:33] op_sel_hi:[1,0]
	v_pk_mul_f32 v[26:27], v[140:141], v[32:33] op_sel_hi:[1,0]
	s_nop 0
	v_cvt_pk_bf16_f32 v26, v26, v27
	v_cvt_pk_bf16_f32 v27, v24, v25
	v_lshl_add_u64 v[24:25], v[34:35], 0, v[178:179]
	global_store_dwordx2 v[24:25], v[26:27], off offset:256
	v_cvt_pk_bf16_f32 v20, v20, v21
	v_cvt_pk_bf16_f32 v21, v22, v23
	v_cvt_pk_bf16_f32 v22, v16, v17
	v_cvt_pk_bf16_f32 v23, v18, v19
	ds_read2_b32 v[16:17], v199 offset0:112 offset1:240
	ds_read2st64_b32 v[18:19], v92 offset0:5 offset1:7
	v_lshlrev_b64 v[24:25], 13, v[184:185]
	v_lshl_add_u64 v[24:25], s[38:39], 0, v[24:25]
	s_waitcnt lgkmcnt(1)
	v_mov_b32_e32 v26, v16
	s_waitcnt lgkmcnt(0)
	v_mov_b32_e32 v27, v18
	v_mov_b32_e32 v18, v17
	v_pk_add_f32 v[16:17], v[26:27], v[18:19]
	s_nop 0
	v_add_f32_e32 v16, v16, v17
	s_waitcnt vmcnt(20)
	v_add_f32_e32 v16, v204, v16
	v_fmamk_f32 v16, v16, 0x3baaaaab, v203
	v_mul_f32_e32 v17, 0x4b800000, v16
	v_cmp_gt_f32_e32 vcc, s66, v16
	s_nop 1
	v_cndmask_b32_e32 v16, v16, v17, vcc
	v_rsq_f32_e32 v18, v16
	v_lshl_add_u64 v[16:17], v[24:25], 0, s[48:49]
	v_lshl_add_u64 v[16:17], v[16:17], 0, v[164:165]
	global_store_dwordx4 v[16:17], v[20:23], off offset:256
	v_mul_f32_e32 v16, 0x45800000, v18
	v_cndmask_b32_e32 v16, v18, v16, vcc
	v_mad_i64_i32 v[18:19], s[54:55], v180, s67, v[182:183]
	v_pk_mul_f32 v[12:13], v[12:13], v[16:17] op_sel_hi:[1,0]
	v_pk_mul_f32 v[8:9], v[8:9], v[16:17] op_sel_hi:[1,0]
	v_pk_mul_f32 v[10:11], v[10:11], v[16:17] op_sel_hi:[1,0]
	v_lshl_add_u64 v[18:19], v[18:19], 0, s[46:47]
	v_pk_mul_f32 v[14:15], v[14:15], v[16:17] op_sel_hi:[1,0]
	v_pk_mul_f32 v[12:13], v[132:133], v[12:13]
	v_pk_mul_f32 v[20:21], v[130:131], v[10:11]
	v_pk_mul_f32 v[10:11], v[128:129], v[8:9]
	v_pk_mul_f32 v[14:15], v[134:135], v[14:15]
	v_cvt_pk_bf16_f32 v8, v12, v13
	v_lshl_add_u64 v[12:13], v[18:19], 0, v[164:165]
	v_cvt_pk_bf16_f32 v9, v14, v15
	v_cvt_pk_bf16_f32 v10, v10, v11
	v_cvt_pk_bf16_f32 v11, v20, v21
	global_store_dwordx4 v[12:13], v[8:11], off
	s_andn2_b64 vcc, exec, s[4:5]
	s_mov_b64 s[4:5], -1
	v_pk_mul_f32 v[8:9], v[138:139], v[16:17] op_sel_hi:[1,0]
	v_pk_mul_f32 v[10:11], v[136:137], v[16:17] op_sel_hi:[1,0]
	s_nop 0
	v_cvt_pk_bf16_f32 v10, v10, v11
	v_cvt_pk_bf16_f32 v11, v8, v9
	v_lshl_add_u64 v[8:9], v[18:19], 0, v[178:179]
	global_store_dwordx2 v[8:9], v[10:11], off offset:256
	v_cvt_pk_bf16_f32 v4, v4, v5
	v_cvt_pk_bf16_f32 v5, v6, v7
	v_cvt_pk_bf16_f32 v6, v0, v1
	v_lshlrev_b64 v[0:1], 13, v[180:181]
	v_lshl_add_u64 v[0:1], s[38:39], 0, v[0:1]
	v_lshl_add_u64 v[0:1], v[0:1], 0, s[48:49]
	v_lshl_add_u64 v[0:1], v[0:1], 0, v[164:165]
	v_cvt_pk_bf16_f32 v7, v2, v3
	global_store_dwordx4 v[0:1], v[4:7], off offset:256
	s_cbranch_vccnz .LBB0_436
	s_andn2_b64 vcc, exec, s[8:9]
	s_cbranch_vccnz .LBB0_435
	s_barrier
	s_branch .LBB0_435
